# stack4 plus: barrier generation / last-arriver tests use the static barrier index (two integer divisions per barrier removed)
# speedup vs baseline: 1.0006x; 1.0006x over previous
.LBB0_80:
	s_or_b64 exec, exec, s[12:13]
	v_cvt_f32_u32_e32 v5, v3
	s_waitcnt vmcnt(0)
	v_readfirstlane_b32 s10, v4
	buffer_inv sc1
	s_add_u32 s8, s8, 0x2400
	s_addc_u32 s9, s9, 0
	v_add_u32_e32 v6, s10, v2
	v_add_u32_e32 v4, 1, v6
	v_mul_u32_u24_e32 v3, 1, v3
	v_mov_b32_e32 v2, 0
	v_cmp_ne_u32_e32 vcc, v4, v3
	s_and_saveexec_b64 s[10:11], vcc
	s_xor_b64 s[10:11], exec, s[10:11]
	s_cbranch_execz .LBB0_94
	s_waitcnt lgkmcnt(0)
	v_mov_b32_e32 v1, 0
	global_load_dword v3, v1, s[8:9] sc1
	s_waitcnt vmcnt(0)
	v_cmp_eq_u32_e32 vcc, v3, v2
	s_and_saveexec_b64 s[12:13], vcc
	s_cbranch_execz .LBB0_93
	s_mov_b32 s24, 1
	s_mov_b64 s[14:15], 0
	s_branch .LBB0_84

.LBB0_97:
	s_or_b64 exec, exec, s[12:13]
	v_cvt_f32_u32_e32 v4, v1
	s_waitcnt vmcnt(0)
	v_readfirstlane_b32 s12, v3
	s_add_u32 s10, s94, 0x7500
	s_addc_u32 s11, s95, 0
	s_mov_b64 s[14:15], -1
	v_add_u32_e32 v2, s12, v2
	v_add_u32_e32 v2, 1, v2
	v_mul_u32_u24_e32 v1, 1, v1
	v_mov_b32_e32 v4, 0
	v_cmp_ne_u32_e32 vcc, v2, v1
	v_mov_b64_e32 v[2:3], s[10:11]
	s_and_saveexec_b64 s[12:13], vcc
	s_cbranch_execz .LBB0_109
	v_mov_b32_e32 v1, 0
	global_load_dword v2, v1, s[100:101] sc1
	s_mov_b64 s[16:17], 0
	s_waitcnt vmcnt(0)
	v_cmp_lt_u32_e32 vcc, v2, v18
	s_and_saveexec_b64 s[14:15], vcc
	s_cbranch_execz .LBB0_108
	s_mov_b32 s26, 1
	s_branch .LBB0_101

.LBB0_174:
	s_or_b64 exec, exec, s[12:13]
	v_cvt_f32_u32_e32 v5, v3
	s_waitcnt vmcnt(0)
	v_readfirstlane_b32 s10, v4
	buffer_inv sc1
	s_add_u32 s8, s8, 0x2400
	s_addc_u32 s9, s9, 0
	v_add_u32_e32 v6, s10, v2
	v_add_u32_e32 v4, 1, v6
	v_mul_u32_u24_e32 v3, 2, v3
	v_mov_b32_e32 v2, 1
	v_cmp_ne_u32_e32 vcc, v4, v3
	s_and_saveexec_b64 s[10:11], vcc
	s_xor_b64 s[10:11], exec, s[10:11]
	s_cbranch_execz .LBB0_188
	s_waitcnt lgkmcnt(0)
	v_mov_b32_e32 v1, 0
	global_load_dword v3, v1, s[8:9] sc1
	s_waitcnt vmcnt(0)
	v_cmp_eq_u32_e32 vcc, v3, v2
	s_and_saveexec_b64 s[12:13], vcc
	s_cbranch_execz .LBB0_187
	s_mov_b32 s24, 1
	s_mov_b64 s[14:15], 0
	s_branch .LBB0_178

.LBB0_191:
	s_or_b64 exec, exec, s[12:13]
	v_cvt_f32_u32_e32 v4, v1
	s_waitcnt vmcnt(0)
	v_readfirstlane_b32 s12, v3
	s_add_u32 s10, s94, 0x7500
	s_addc_u32 s11, s95, 0
	s_mov_b64 s[14:15], -1
	v_add_u32_e32 v2, s12, v2
	v_add_u32_e32 v2, 1, v2
	v_mul_u32_u24_e32 v1, 2, v1
	v_mov_b32_e32 v4, 1
	v_cmp_ne_u32_e32 vcc, v2, v1
	v_mov_b64_e32 v[2:3], s[10:11]
	s_and_saveexec_b64 s[12:13], vcc
	s_cbranch_execz .LBB0_203
	v_mov_b32_e32 v1, 0
	global_load_dword v2, v1, s[100:101] sc1
	s_mov_b64 s[16:17], 0
	s_waitcnt vmcnt(0)
	v_cmp_lt_u32_e32 vcc, v2, v18
	s_and_saveexec_b64 s[14:15], vcc
	s_cbranch_execz .LBB0_202
	s_mov_b32 s26, 1
	s_branch .LBB0_195

.LBB0_271:
	s_or_b64 exec, exec, s[12:13]
	v_cvt_f32_u32_e32 v5, v3
	s_waitcnt vmcnt(0)
	v_readfirstlane_b32 s10, v4
	buffer_inv sc1
	s_add_u32 s8, s8, 0x2400
	s_addc_u32 s9, s9, 0
	v_add_u32_e32 v6, s10, v2
	v_add_u32_e32 v4, 1, v6
	v_mul_u32_u24_e32 v3, 3, v3
	v_mov_b32_e32 v2, 2
	v_cmp_ne_u32_e32 vcc, v4, v3
	s_and_saveexec_b64 s[10:11], vcc
	s_xor_b64 s[10:11], exec, s[10:11]
	s_cbranch_execz .LBB0_285
	s_waitcnt lgkmcnt(0)
	v_mov_b32_e32 v1, 0
	global_load_dword v3, v1, s[8:9] sc1
	s_waitcnt vmcnt(0)
	v_cmp_eq_u32_e32 vcc, v3, v2
	s_and_saveexec_b64 s[12:13], vcc
	s_cbranch_execz .LBB0_284
	s_mov_b32 s24, 1
	s_mov_b64 s[14:15], 0
	s_branch .LBB0_275

.LBB0_288:
	s_or_b64 exec, exec, s[12:13]
	v_cvt_f32_u32_e32 v4, v1
	s_waitcnt vmcnt(0)
	v_readfirstlane_b32 s12, v3
	s_add_u32 s10, s94, 0x7500
	s_addc_u32 s11, s95, 0
	s_mov_b64 s[14:15], -1
	v_add_u32_e32 v2, s12, v2
	v_add_u32_e32 v2, 1, v2
	v_mul_u32_u24_e32 v1, 3, v1
	v_mov_b32_e32 v4, 2
	v_cmp_ne_u32_e32 vcc, v2, v1
	v_mov_b64_e32 v[2:3], s[10:11]
	s_and_saveexec_b64 s[12:13], vcc
	s_cbranch_execz .LBB0_300
	v_mov_b32_e32 v1, 0
	global_load_dword v2, v1, s[100:101] sc1
	s_mov_b64 s[16:17], 0
	s_waitcnt vmcnt(0)
	v_cmp_lt_u32_e32 vcc, v2, v18
	s_and_saveexec_b64 s[14:15], vcc
	s_cbranch_execz .LBB0_299
	s_mov_b32 s26, 1
	s_branch .LBB0_292

.LBB0_343:
	s_or_b64 exec, exec, s[12:13]
	v_cvt_f32_u32_e32 v5, v3
	s_waitcnt vmcnt(0)
	v_readfirstlane_b32 s10, v4
	buffer_inv sc1
	s_add_u32 s8, s8, 0x2400
	s_addc_u32 s9, s9, 0
	v_add_u32_e32 v6, s10, v2
	v_add_u32_e32 v4, 1, v6
	v_mul_u32_u24_e32 v3, 4, v3
	v_mov_b32_e32 v2, 3
	v_cmp_ne_u32_e32 vcc, v4, v3
	s_and_saveexec_b64 s[10:11], vcc
	s_xor_b64 s[10:11], exec, s[10:11]
	s_cbranch_execz .LBB0_357
	s_waitcnt lgkmcnt(0)
	v_mov_b32_e32 v1, 0
	global_load_dword v3, v1, s[8:9] sc1
	s_waitcnt vmcnt(0)
	v_cmp_eq_u32_e32 vcc, v3, v2
	s_and_saveexec_b64 s[12:13], vcc
	s_cbranch_execz .LBB0_356
	s_mov_b32 s24, 1
	s_mov_b64 s[14:15], 0
	s_branch .LBB0_347

.LBB0_360:
	s_or_b64 exec, exec, s[12:13]
	v_cvt_f32_u32_e32 v4, v1
	s_waitcnt vmcnt(0)
	v_readfirstlane_b32 s12, v3
	s_add_u32 s10, s94, 0x7500
	s_addc_u32 s11, s95, 0
	s_mov_b64 s[14:15], -1
	v_add_u32_e32 v2, s12, v2
	v_add_u32_e32 v2, 1, v2
	v_mul_u32_u24_e32 v1, 4, v1
	v_mov_b32_e32 v4, 3
	v_cmp_ne_u32_e32 vcc, v2, v1
	v_mov_b64_e32 v[2:3], s[10:11]
	s_and_saveexec_b64 s[12:13], vcc
	s_cbranch_execz .LBB0_372
	v_mov_b32_e32 v1, 0
	global_load_dword v2, v1, s[100:101] sc1
	s_mov_b64 s[16:17], 0
	s_waitcnt vmcnt(0)
	v_cmp_lt_u32_e32 vcc, v2, v18
	s_and_saveexec_b64 s[14:15], vcc
	s_cbranch_execz .LBB0_371
	s_mov_b32 s26, 1
	s_branch .LBB0_364

.LBB0_442:
	s_or_b64 exec, exec, s[12:13]
	v_cvt_f32_u32_e32 v5, v3
	s_waitcnt vmcnt(0)
	v_readfirstlane_b32 s10, v4
	buffer_inv sc1
	s_add_u32 s8, s8, 0x2400
	s_addc_u32 s9, s9, 0
	v_add_u32_e32 v6, s10, v2
	v_add_u32_e32 v4, 1, v6
	v_mul_u32_u24_e32 v3, 5, v3
	v_mov_b32_e32 v2, 4
	v_cmp_ne_u32_e32 vcc, v4, v3
	s_and_saveexec_b64 s[10:11], vcc
	s_xor_b64 s[10:11], exec, s[10:11]
	s_cbranch_execz .LBB0_456
	s_waitcnt lgkmcnt(0)
	v_mov_b32_e32 v1, 0
	global_load_dword v3, v1, s[8:9] sc1
	s_waitcnt vmcnt(0)
	v_cmp_eq_u32_e32 vcc, v3, v2
	s_and_saveexec_b64 s[12:13], vcc
	s_cbranch_execz .LBB0_455
	s_mov_b32 s24, 1
	s_mov_b64 s[14:15], 0
	s_branch .LBB0_446

.LBB0_459:
	s_or_b64 exec, exec, s[12:13]
	v_cvt_f32_u32_e32 v4, v1
	s_waitcnt vmcnt(0)
	v_readfirstlane_b32 s12, v3
	s_add_u32 s10, s94, 0x7500
	s_addc_u32 s11, s95, 0
	s_mov_b64 s[14:15], -1
	v_add_u32_e32 v2, s12, v2
	v_add_u32_e32 v2, 1, v2
	v_mul_u32_u24_e32 v1, 5, v1
	v_mov_b32_e32 v4, 4
	v_cmp_ne_u32_e32 vcc, v2, v1
	v_mov_b64_e32 v[2:3], s[10:11]
	s_and_saveexec_b64 s[12:13], vcc
	s_cbranch_execz .LBB0_471
	v_mov_b32_e32 v1, 0
	global_load_dword v2, v1, s[100:101] sc1
	s_mov_b64 s[16:17], 0
	s_waitcnt vmcnt(0)
	v_cmp_lt_u32_e32 vcc, v2, v18
	s_and_saveexec_b64 s[14:15], vcc
	s_cbranch_execz .LBB0_470
	s_mov_b32 s26, 1
	s_branch .LBB0_463

.LBB0_519:
	s_or_b64 exec, exec, s[12:13]
	v_cvt_f32_u32_e32 v5, v3
	s_waitcnt vmcnt(0)
	v_readfirstlane_b32 s10, v4
	buffer_inv sc1
	s_add_u32 s8, s8, 0x2400
	s_addc_u32 s9, s9, 0
	v_add_u32_e32 v6, s10, v2
	v_add_u32_e32 v4, 1, v6
	v_mul_u32_u24_e32 v3, 6, v3
	v_mov_b32_e32 v2, 5
	v_cmp_ne_u32_e32 vcc, v4, v3
	s_and_saveexec_b64 s[10:11], vcc
	s_xor_b64 s[10:11], exec, s[10:11]
	s_cbranch_execz .LBB0_533
	s_waitcnt lgkmcnt(0)
	v_mov_b32_e32 v1, 0
	global_load_dword v3, v1, s[8:9] sc1
	s_waitcnt vmcnt(0)
	v_cmp_eq_u32_e32 vcc, v3, v2
	s_and_saveexec_b64 s[12:13], vcc
	s_cbranch_execz .LBB0_532
	s_mov_b32 s24, 1
	s_mov_b64 s[14:15], 0
	s_branch .LBB0_523

.LBB0_536:
	s_or_b64 exec, exec, s[12:13]
	v_cvt_f32_u32_e32 v4, v1
	s_waitcnt vmcnt(0)
	v_readfirstlane_b32 s12, v3
	s_add_u32 s10, s94, 0x7500
	s_addc_u32 s11, s95, 0
	s_mov_b64 s[14:15], -1
	v_add_u32_e32 v2, s12, v2
	v_add_u32_e32 v2, 1, v2
	v_mul_u32_u24_e32 v1, 6, v1
	v_mov_b32_e32 v4, 5
	v_cmp_ne_u32_e32 vcc, v2, v1
	v_mov_b64_e32 v[2:3], s[10:11]
	s_and_saveexec_b64 s[12:13], vcc
	s_cbranch_execz .LBB0_548
	v_mov_b32_e32 v1, 0
	global_load_dword v2, v1, s[100:101] sc1
	s_mov_b64 s[16:17], 0
	s_waitcnt vmcnt(0)
	v_cmp_lt_u32_e32 vcc, v2, v18
	s_and_saveexec_b64 s[14:15], vcc
	s_cbranch_execz .LBB0_547
	s_mov_b32 s26, 1
	s_branch .LBB0_540

.LBB0_600:
	s_or_b64 exec, exec, s[12:13]
	v_cvt_f32_u32_e32 v5, v3
	s_waitcnt vmcnt(0)
	v_readfirstlane_b32 s10, v4
	buffer_inv sc1
	s_add_u32 s8, s8, 0x2400
	s_addc_u32 s9, s9, 0
	v_add_u32_e32 v6, s10, v2
	v_add_u32_e32 v4, 1, v6
	v_mul_u32_u24_e32 v3, 7, v3
	v_mov_b32_e32 v2, 6
	v_cmp_ne_u32_e32 vcc, v4, v3
	s_and_saveexec_b64 s[10:11], vcc
	s_xor_b64 s[10:11], exec, s[10:11]
	s_cbranch_execz .LBB0_614
	s_waitcnt lgkmcnt(0)
	v_mov_b32_e32 v1, 0
	global_load_dword v3, v1, s[8:9] sc1
	s_waitcnt vmcnt(0)
	v_cmp_eq_u32_e32 vcc, v3, v2
	s_and_saveexec_b64 s[12:13], vcc
	s_cbranch_execz .LBB0_613
	s_mov_b32 s24, 1
	s_mov_b64 s[14:15], 0
	s_branch .LBB0_604

.LBB0_617:
	s_or_b64 exec, exec, s[12:13]
	v_cvt_f32_u32_e32 v4, v1
	s_waitcnt vmcnt(0)
	v_readfirstlane_b32 s12, v3
	s_add_u32 s10, s94, 0x7500
	s_addc_u32 s11, s95, 0
	s_mov_b64 s[14:15], -1
	v_add_u32_e32 v2, s12, v2
	v_add_u32_e32 v2, 1, v2
	v_mul_u32_u24_e32 v1, 7, v1
	v_mov_b32_e32 v4, 6
	v_cmp_ne_u32_e32 vcc, v2, v1
	v_mov_b64_e32 v[2:3], s[10:11]
	s_and_saveexec_b64 s[12:13], vcc
	s_cbranch_execz .LBB0_629
	v_mov_b32_e32 v1, 0
	global_load_dword v2, v1, s[100:101] sc1
	s_mov_b64 s[16:17], 0
	s_waitcnt vmcnt(0)
	v_cmp_lt_u32_e32 vcc, v2, v18
	s_and_saveexec_b64 s[14:15], vcc
	s_cbranch_execz .LBB0_628
	s_mov_b32 s26, 1
	s_branch .LBB0_621

.LBB0_680:
	s_or_b64 exec, exec, s[12:13]
	v_cvt_f32_u32_e32 v5, v3
	s_waitcnt vmcnt(0)
	v_readfirstlane_b32 s10, v4
	buffer_inv sc1
	s_add_u32 s8, s8, 0x2400
	s_addc_u32 s9, s9, 0
	v_add_u32_e32 v6, s10, v2
	v_add_u32_e32 v4, 1, v6
	v_mul_u32_u24_e32 v3, 8, v3
	v_mov_b32_e32 v2, 7
	v_cmp_ne_u32_e32 vcc, v4, v3
	s_and_saveexec_b64 s[10:11], vcc
	s_xor_b64 s[10:11], exec, s[10:11]
	s_cbranch_execz .LBB0_694
	s_waitcnt lgkmcnt(0)
	v_mov_b32_e32 v1, 0
	global_load_dword v3, v1, s[8:9] sc1
	s_waitcnt vmcnt(0)
	v_cmp_eq_u32_e32 vcc, v3, v2
	s_and_saveexec_b64 s[12:13], vcc
	s_cbranch_execz .LBB0_693
	s_mov_b32 s24, 1
	s_mov_b64 s[14:15], 0
	s_branch .LBB0_684

.LBB0_697:
	s_or_b64 exec, exec, s[12:13]
	v_cvt_f32_u32_e32 v4, v1
	s_waitcnt vmcnt(0)
	v_readfirstlane_b32 s12, v3
	s_add_u32 s10, s94, 0x7500
	s_addc_u32 s11, s95, 0
	s_mov_b64 s[14:15], -1
	v_add_u32_e32 v2, s12, v2
	v_add_u32_e32 v2, 1, v2
	v_mul_u32_u24_e32 v1, 8, v1
	v_mov_b32_e32 v4, 7
	v_cmp_ne_u32_e32 vcc, v2, v1
	v_mov_b64_e32 v[2:3], s[10:11]
	s_and_saveexec_b64 s[12:13], vcc
	s_cbranch_execz .LBB0_709
	v_mov_b32_e32 v1, 0
	global_load_dword v2, v1, s[100:101] sc1
	s_mov_b64 s[16:17], 0
	s_waitcnt vmcnt(0)
	v_cmp_lt_u32_e32 vcc, v2, v18
	s_and_saveexec_b64 s[14:15], vcc
	s_cbranch_execz .LBB0_708
	s_mov_b32 s26, 1
	s_branch .LBB0_701

.LBB0_774:
	s_or_b64 exec, exec, s[12:13]
	v_cvt_f32_u32_e32 v5, v3
	s_waitcnt vmcnt(0)
	v_readfirstlane_b32 s10, v4
	buffer_inv sc1
	s_add_u32 s8, s8, 0x2400
	s_addc_u32 s9, s9, 0
	v_add_u32_e32 v6, s10, v2
	v_add_u32_e32 v4, 1, v6
	v_mul_u32_u24_e32 v3, 9, v3
	v_mov_b32_e32 v2, 8
	v_cmp_ne_u32_e32 vcc, v4, v3
	s_and_saveexec_b64 s[10:11], vcc
	s_xor_b64 s[10:11], exec, s[10:11]
	s_cbranch_execz .LBB0_788
	s_waitcnt lgkmcnt(0)
	v_mov_b32_e32 v1, 0
	global_load_dword v3, v1, s[8:9] sc1
	s_waitcnt vmcnt(0)
	v_cmp_eq_u32_e32 vcc, v3, v2
	s_and_saveexec_b64 s[12:13], vcc
	s_cbranch_execz .LBB0_787
	s_mov_b32 s24, 1
	s_mov_b64 s[14:15], 0
	s_branch .LBB0_778

.LBB0_791:
	s_or_b64 exec, exec, s[12:13]
	v_cvt_f32_u32_e32 v4, v1
	s_waitcnt vmcnt(0)
	v_readfirstlane_b32 s12, v3
	s_add_u32 s10, s94, 0x7500
	s_addc_u32 s11, s95, 0
	s_mov_b64 s[14:15], -1
	v_add_u32_e32 v2, s12, v2
	v_add_u32_e32 v2, 1, v2
	v_mul_u32_u24_e32 v1, 9, v1
	v_mov_b32_e32 v4, 8
	v_cmp_ne_u32_e32 vcc, v2, v1
	v_mov_b64_e32 v[2:3], s[10:11]
	s_and_saveexec_b64 s[12:13], vcc
	s_cbranch_execz .LBB0_803
	v_mov_b32_e32 v1, 0
	global_load_dword v2, v1, s[100:101] sc1
	s_mov_b64 s[16:17], 0
	s_waitcnt vmcnt(0)
	v_cmp_lt_u32_e32 vcc, v2, v18
	s_and_saveexec_b64 s[14:15], vcc
	s_cbranch_execz .LBB0_802
	s_mov_b32 s26, 1
	s_branch .LBB0_795

.LBB0_871:
	s_or_b64 exec, exec, s[12:13]
	v_cvt_f32_u32_e32 v5, v3
	s_waitcnt vmcnt(0)
	v_readfirstlane_b32 s10, v4
	buffer_inv sc1
	s_add_u32 s8, s8, 0x2400
	s_addc_u32 s9, s9, 0
	v_add_u32_e32 v6, s10, v2
	v_add_u32_e32 v4, 1, v6
	v_mul_u32_u24_e32 v3, 10, v3
	v_mov_b32_e32 v2, 9
	v_cmp_ne_u32_e32 vcc, v4, v3
	s_and_saveexec_b64 s[10:11], vcc
	s_xor_b64 s[10:11], exec, s[10:11]
	s_cbranch_execz .LBB0_885
	s_waitcnt lgkmcnt(0)
	v_mov_b32_e32 v1, 0
	global_load_dword v3, v1, s[8:9] sc1
	s_waitcnt vmcnt(0)
	v_cmp_eq_u32_e32 vcc, v3, v2
	s_and_saveexec_b64 s[12:13], vcc
	s_cbranch_execz .LBB0_884
	s_mov_b32 s24, 1
	s_mov_b64 s[14:15], 0
	s_branch .LBB0_875

.LBB0_888:
	s_or_b64 exec, exec, s[12:13]
	v_cvt_f32_u32_e32 v4, v1
	s_waitcnt vmcnt(0)
	v_readfirstlane_b32 s12, v3
	s_add_u32 s10, s94, 0x7500
	s_addc_u32 s11, s95, 0
	s_mov_b64 s[14:15], -1
	v_add_u32_e32 v2, s12, v2
	v_add_u32_e32 v2, 1, v2
	v_mul_u32_u24_e32 v1, 10, v1
	v_mov_b32_e32 v4, 9
	v_cmp_ne_u32_e32 vcc, v2, v1
	v_mov_b64_e32 v[2:3], s[10:11]
	s_and_saveexec_b64 s[12:13], vcc
	s_cbranch_execz .LBB0_900
	v_mov_b32_e32 v1, 0
	global_load_dword v2, v1, s[100:101] sc1
	s_mov_b64 s[16:17], 0
	s_waitcnt vmcnt(0)
	v_cmp_lt_u32_e32 vcc, v2, v18
	s_and_saveexec_b64 s[14:15], vcc
	s_cbranch_execz .LBB0_899
	s_mov_b32 s26, 1
	s_branch .LBB0_892

.LBB0_951:
	s_or_b64 exec, exec, s[12:13]
	v_cvt_f32_u32_e32 v5, v3
	s_waitcnt vmcnt(0)
	v_readfirstlane_b32 s10, v4
	buffer_inv sc1
	s_add_u32 s8, s8, 0x2400
	s_addc_u32 s9, s9, 0
	v_add_u32_e32 v6, s10, v2
	v_add_u32_e32 v4, 1, v6
	v_mul_u32_u24_e32 v3, 11, v3
	v_mov_b32_e32 v2, 10
	v_cmp_ne_u32_e32 vcc, v4, v3
	s_and_saveexec_b64 s[10:11], vcc
	s_xor_b64 s[10:11], exec, s[10:11]
	s_cbranch_execz .LBB0_965
	s_waitcnt lgkmcnt(0)
	v_mov_b32_e32 v1, 0
	global_load_dword v3, v1, s[8:9] sc1
	s_waitcnt vmcnt(0)
	v_cmp_eq_u32_e32 vcc, v3, v2
	s_and_saveexec_b64 s[12:13], vcc
	s_cbranch_execz .LBB0_964
	s_mov_b32 s24, 1
	s_mov_b64 s[14:15], 0
	s_branch .LBB0_955

.LBB0_968:
	s_or_b64 exec, exec, s[12:13]
	v_cvt_f32_u32_e32 v4, v1
	s_waitcnt vmcnt(0)
	v_readfirstlane_b32 s12, v3
	s_add_u32 s10, s94, 0x7500
	s_addc_u32 s11, s95, 0
	s_mov_b64 s[14:15], -1
	v_add_u32_e32 v2, s12, v2
	v_add_u32_e32 v2, 1, v2
	v_mul_u32_u24_e32 v1, 11, v1
	v_mov_b32_e32 v4, 10
	v_cmp_ne_u32_e32 vcc, v2, v1
	v_mov_b64_e32 v[2:3], s[10:11]
	s_and_saveexec_b64 s[12:13], vcc
	s_cbranch_execz .LBB0_980
	v_mov_b32_e32 v1, 0
	global_load_dword v2, v1, s[100:101] sc1
	s_mov_b64 s[16:17], 0
	s_waitcnt vmcnt(0)
	v_cmp_lt_u32_e32 vcc, v2, v18
	s_and_saveexec_b64 s[14:15], vcc
	s_cbranch_execz .LBB0_979
	s_mov_b32 s26, 1
	s_branch .LBB0_972

.LBB0_1045:
	s_or_b64 exec, exec, s[12:13]
	v_cvt_f32_u32_e32 v5, v3
	s_waitcnt vmcnt(0)
	v_readfirstlane_b32 s10, v4
	buffer_inv sc1
	s_add_u32 s8, s8, 0x2400
	s_addc_u32 s9, s9, 0
	v_add_u32_e32 v6, s10, v2
	v_add_u32_e32 v4, 1, v6
	v_mul_u32_u24_e32 v3, 12, v3
	v_mov_b32_e32 v2, 11
	v_cmp_ne_u32_e32 vcc, v4, v3
	s_and_saveexec_b64 s[10:11], vcc
	s_xor_b64 s[10:11], exec, s[10:11]
	s_cbranch_execz .LBB0_1059
	s_waitcnt lgkmcnt(0)
	v_mov_b32_e32 v1, 0
	global_load_dword v3, v1, s[8:9] sc1
	s_waitcnt vmcnt(0)
	v_cmp_eq_u32_e32 vcc, v3, v2
	s_and_saveexec_b64 s[12:13], vcc
	s_cbranch_execz .LBB0_1058
	s_mov_b32 s24, 1
	s_mov_b64 s[14:15], 0
	s_branch .LBB0_1049

.LBB0_1062:
	s_or_b64 exec, exec, s[12:13]
	v_cvt_f32_u32_e32 v4, v1
	s_waitcnt vmcnt(0)
	v_readfirstlane_b32 s12, v3
	s_add_u32 s10, s94, 0x7500
	s_addc_u32 s11, s95, 0
	s_mov_b64 s[14:15], -1
	v_add_u32_e32 v2, s12, v2
	v_add_u32_e32 v2, 1, v2
	v_mul_u32_u24_e32 v1, 12, v1
	v_mov_b32_e32 v4, 11
	v_cmp_ne_u32_e32 vcc, v2, v1
	v_mov_b64_e32 v[2:3], s[10:11]
	s_and_saveexec_b64 s[12:13], vcc
	s_cbranch_execz .LBB0_1074
	v_mov_b32_e32 v1, 0
	global_load_dword v2, v1, s[100:101] sc1
	s_mov_b64 s[16:17], 0
	s_waitcnt vmcnt(0)
	v_cmp_lt_u32_e32 vcc, v2, v18
	s_and_saveexec_b64 s[14:15], vcc
	s_cbranch_execz .LBB0_1073
	s_mov_b32 s26, 1
	s_branch .LBB0_1066

.LBB0_1142:
	s_or_b64 exec, exec, s[12:13]
	v_cvt_f32_u32_e32 v5, v3
	s_waitcnt vmcnt(0)
	v_readfirstlane_b32 s10, v4
	buffer_inv sc1
	s_add_u32 s8, s8, 0x2400
	s_addc_u32 s9, s9, 0
	v_add_u32_e32 v6, s10, v2
	v_add_u32_e32 v4, 1, v6
	v_mul_u32_u24_e32 v3, 13, v3
	v_mov_b32_e32 v2, 12
	v_cmp_ne_u32_e32 vcc, v4, v3
	s_and_saveexec_b64 s[10:11], vcc
	s_xor_b64 s[10:11], exec, s[10:11]
	s_cbranch_execz .LBB0_1156
	s_waitcnt lgkmcnt(0)
	v_mov_b32_e32 v1, 0
	global_load_dword v3, v1, s[8:9] sc1
	s_waitcnt vmcnt(0)
	v_cmp_eq_u32_e32 vcc, v3, v2
	s_and_saveexec_b64 s[12:13], vcc
	s_cbranch_execz .LBB0_1155
	s_mov_b32 s24, 1
	s_mov_b64 s[14:15], 0
	s_branch .LBB0_1146

.LBB0_1159:
	s_or_b64 exec, exec, s[12:13]
	v_cvt_f32_u32_e32 v4, v1
	s_waitcnt vmcnt(0)
	v_readfirstlane_b32 s12, v3
	s_add_u32 s10, s94, 0x7500
	s_addc_u32 s11, s95, 0
	s_mov_b64 s[14:15], -1
	v_add_u32_e32 v2, s12, v2
	v_add_u32_e32 v2, 1, v2
	v_mul_u32_u24_e32 v1, 13, v1
	v_mov_b32_e32 v4, 12
	v_cmp_ne_u32_e32 vcc, v2, v1
	v_mov_b64_e32 v[2:3], s[10:11]
	s_and_saveexec_b64 s[12:13], vcc
	s_cbranch_execz .LBB0_1171
	v_mov_b32_e32 v1, 0
	global_load_dword v2, v1, s[100:101] sc1
	s_mov_b64 s[16:17], 0
	s_waitcnt vmcnt(0)
	v_cmp_lt_u32_e32 vcc, v2, v18
	s_and_saveexec_b64 s[14:15], vcc
	s_cbranch_execz .LBB0_1170
	s_mov_b32 s26, 1
	s_branch .LBB0_1163

.LBB0_1214:
	s_or_b64 exec, exec, s[12:13]
	v_cvt_f32_u32_e32 v5, v3
	s_waitcnt vmcnt(0)
	v_readfirstlane_b32 s10, v4
	buffer_inv sc1
	s_add_u32 s8, s8, 0x2400
	s_addc_u32 s9, s9, 0
	v_add_u32_e32 v6, s10, v2
	v_add_u32_e32 v4, 1, v6
	v_mul_u32_u24_e32 v3, 14, v3
	v_mov_b32_e32 v2, 13
	v_cmp_ne_u32_e32 vcc, v4, v3
	s_and_saveexec_b64 s[10:11], vcc
	s_xor_b64 s[10:11], exec, s[10:11]
	s_cbranch_execz .LBB0_1228
	s_waitcnt lgkmcnt(0)
	v_mov_b32_e32 v1, 0
	global_load_dword v3, v1, s[8:9] sc1
	s_waitcnt vmcnt(0)
	v_cmp_eq_u32_e32 vcc, v3, v2
	s_and_saveexec_b64 s[12:13], vcc
	s_cbranch_execz .LBB0_1227
	s_mov_b32 s24, 1
	s_mov_b64 s[14:15], 0
	s_branch .LBB0_1218

.LBB0_1231:
	s_or_b64 exec, exec, s[12:13]
	v_cvt_f32_u32_e32 v4, v1
	s_waitcnt vmcnt(0)
	v_readfirstlane_b32 s12, v3
	s_add_u32 s10, s94, 0x7500
	s_addc_u32 s11, s95, 0
	s_mov_b64 s[14:15], -1
	v_add_u32_e32 v2, s12, v2
	v_add_u32_e32 v2, 1, v2
	v_mul_u32_u24_e32 v1, 14, v1
	v_mov_b32_e32 v4, 13
	v_cmp_ne_u32_e32 vcc, v2, v1
	v_mov_b64_e32 v[2:3], s[10:11]
	s_and_saveexec_b64 s[12:13], vcc
	s_cbranch_execz .LBB0_1243
	v_mov_b32_e32 v1, 0
	global_load_dword v2, v1, s[100:101] sc1
	s_mov_b64 s[16:17], 0
	s_waitcnt vmcnt(0)
	v_cmp_lt_u32_e32 vcc, v2, v18
	s_and_saveexec_b64 s[14:15], vcc
	s_cbranch_execz .LBB0_1242
	s_mov_b32 s26, 1
	s_branch .LBB0_1235

.LBB0_1291:
	s_or_b64 exec, exec, s[12:13]
	v_cvt_f32_u32_e32 v5, v3
	s_waitcnt vmcnt(0)
	v_readfirstlane_b32 s10, v4
	buffer_inv sc1
	s_add_u32 s8, s8, 0x2400
	s_addc_u32 s9, s9, 0
	v_add_u32_e32 v6, s10, v2
	v_add_u32_e32 v4, 1, v6
	v_mul_u32_u24_e32 v3, 15, v3
	v_mov_b32_e32 v2, 14
	v_cmp_ne_u32_e32 vcc, v4, v3
	s_and_saveexec_b64 s[10:11], vcc
	s_xor_b64 s[10:11], exec, s[10:11]
	s_cbranch_execz .LBB0_1305
	s_waitcnt lgkmcnt(0)
	v_mov_b32_e32 v1, 0
	global_load_dword v3, v1, s[8:9] sc1
	s_waitcnt vmcnt(0)
	v_cmp_eq_u32_e32 vcc, v3, v2
	s_and_saveexec_b64 s[12:13], vcc
	s_cbranch_execz .LBB0_1304
	s_mov_b32 s24, 1
	s_mov_b64 s[14:15], 0
	s_branch .LBB0_1295

.LBB0_1308:
	s_or_b64 exec, exec, s[12:13]
	v_cvt_f32_u32_e32 v4, v1
	s_waitcnt vmcnt(0)
	v_readfirstlane_b32 s12, v3
	s_add_u32 s10, s94, 0x7500
	s_addc_u32 s11, s95, 0
	s_mov_b64 s[14:15], -1
	v_add_u32_e32 v2, s12, v2
	v_add_u32_e32 v2, 1, v2
	v_mul_u32_u24_e32 v1, 15, v1
	v_mov_b32_e32 v4, 14
	v_cmp_ne_u32_e32 vcc, v2, v1
	v_mov_b64_e32 v[2:3], s[10:11]
	s_and_saveexec_b64 s[12:13], vcc
	s_cbranch_execz .LBB0_1320
	v_mov_b32_e32 v1, 0
	global_load_dword v2, v1, s[100:101] sc1
	s_mov_b64 s[16:17], 0
	s_waitcnt vmcnt(0)
	v_cmp_lt_u32_e32 vcc, v2, v18
	s_and_saveexec_b64 s[14:15], vcc
	s_cbranch_execz .LBB0_1319
	s_mov_b32 s26, 1
	s_branch .LBB0_1312

.LBB0_1377:
	s_or_b64 exec, exec, s[12:13]
	v_cvt_f32_u32_e32 v5, v3
	s_waitcnt vmcnt(0)
	v_readfirstlane_b32 s10, v4
	buffer_inv sc1
	s_add_u32 s8, s8, 0x2400
	s_addc_u32 s9, s9, 0
	v_add_u32_e32 v6, s10, v2
	v_add_u32_e32 v4, 1, v6
	v_mul_u32_u24_e32 v3, 16, v3
	v_mov_b32_e32 v2, 15
	v_cmp_ne_u32_e32 vcc, v4, v3
	s_and_saveexec_b64 s[10:11], vcc
	s_xor_b64 s[10:11], exec, s[10:11]
	s_cbranch_execz .LBB0_1391
	s_waitcnt lgkmcnt(0)
	v_mov_b32_e32 v1, 0
	global_load_dword v3, v1, s[8:9] sc1
	s_waitcnt vmcnt(0)
	v_cmp_eq_u32_e32 vcc, v3, v2
	s_and_saveexec_b64 s[12:13], vcc
	s_cbranch_execz .LBB0_1390
	s_mov_b32 s26, 1
	s_mov_b64 s[14:15], 0
	s_branch .LBB0_1381

.LBB0_1394:
	s_or_b64 exec, exec, s[12:13]
	v_cvt_f32_u32_e32 v4, v1
	s_waitcnt vmcnt(0)
	v_readfirstlane_b32 s12, v3
	s_add_u32 s10, s94, 0x7500
	s_addc_u32 s11, s95, 0
	s_mov_b64 s[14:15], -1
	v_add_u32_e32 v2, s12, v2
	v_add_u32_e32 v2, 1, v2
	v_mul_u32_u24_e32 v1, 16, v1
	v_mov_b32_e32 v4, 15
	v_cmp_ne_u32_e32 vcc, v2, v1
	v_mov_b64_e32 v[2:3], s[10:11]
	s_and_saveexec_b64 s[12:13], vcc
	s_cbranch_execz .LBB0_1406
	v_mov_b32_e32 v1, 0
	global_load_dword v2, v1, s[100:101] sc1
	s_mov_b64 s[16:17], 0
	s_waitcnt vmcnt(0)
	v_cmp_lt_u32_e32 vcc, v2, v18
	s_and_saveexec_b64 s[14:15], vcc
	s_cbranch_execz .LBB0_1405
	s_mov_b32 s28, 1
	s_branch .LBB0_1398

.LBB0_1458:
	s_or_b64 exec, exec, s[12:13]
	v_cvt_f32_u32_e32 v5, v3
	s_waitcnt vmcnt(0)
	v_readfirstlane_b32 s10, v4
	buffer_inv sc1
	s_add_u32 s8, s8, 0x2400
	s_addc_u32 s9, s9, 0
	v_add_u32_e32 v6, s10, v2
	v_add_u32_e32 v4, 1, v6
	v_mul_u32_u24_e32 v3, 17, v3
	v_mov_b32_e32 v2, 16
	v_cmp_ne_u32_e32 vcc, v4, v3
	s_and_saveexec_b64 s[10:11], vcc
	s_xor_b64 s[10:11], exec, s[10:11]
	s_cbranch_execz .LBB0_1472
	s_waitcnt lgkmcnt(0)
	v_mov_b32_e32 v1, 0
	global_load_dword v3, v1, s[8:9] sc1
	s_waitcnt vmcnt(0)
	v_cmp_eq_u32_e32 vcc, v3, v2
	s_and_saveexec_b64 s[12:13], vcc
	s_cbranch_execz .LBB0_1471
	s_mov_b32 s26, 1
	s_mov_b64 s[14:15], 0
	s_branch .LBB0_1462

.LBB0_1475:
	s_or_b64 exec, exec, s[12:13]
	v_cvt_f32_u32_e32 v4, v1
	s_waitcnt vmcnt(0)
	v_readfirstlane_b32 s12, v3
	s_add_u32 s10, s94, 0x7500
	s_addc_u32 s11, s95, 0
	s_mov_b64 s[14:15], -1
	v_add_u32_e32 v2, s12, v2
	v_add_u32_e32 v2, 1, v2
	v_mul_u32_u24_e32 v1, 17, v1
	v_mov_b32_e32 v4, 16
	v_cmp_ne_u32_e32 vcc, v2, v1
	v_mov_b64_e32 v[2:3], s[10:11]
	s_and_saveexec_b64 s[12:13], vcc
	s_cbranch_execz .LBB0_1487
	v_mov_b32_e32 v1, 0
	global_load_dword v2, v1, s[100:101] sc1
	s_mov_b64 s[16:17], 0
	s_waitcnt vmcnt(0)
	v_cmp_lt_u32_e32 vcc, v2, v18
	s_and_saveexec_b64 s[14:15], vcc
	s_cbranch_execz .LBB0_1486
	s_mov_b32 s28, 1
	s_branch .LBB0_1479

.LBB0_1538:
	s_or_b64 exec, exec, s[12:13]
	v_cvt_f32_u32_e32 v5, v3
	s_waitcnt vmcnt(0)
	v_readfirstlane_b32 s10, v4
	buffer_inv sc1
	s_add_u32 s8, s8, 0x2400
	s_addc_u32 s9, s9, 0
	v_add_u32_e32 v6, s10, v2
	v_add_u32_e32 v4, 1, v6
	v_mul_u32_u24_e32 v3, 18, v3
	v_mov_b32_e32 v2, 17
	v_cmp_ne_u32_e32 vcc, v4, v3
	s_and_saveexec_b64 s[10:11], vcc
	s_xor_b64 s[10:11], exec, s[10:11]
	s_cbranch_execz .LBB0_1552
	s_waitcnt lgkmcnt(0)
	v_mov_b32_e32 v1, 0
	global_load_dword v3, v1, s[8:9] sc1
	s_waitcnt vmcnt(0)
	v_cmp_eq_u32_e32 vcc, v3, v2
	s_and_saveexec_b64 s[12:13], vcc
	s_cbranch_execz .LBB0_1551
	s_mov_b32 s26, 1
	s_mov_b64 s[14:15], 0
	s_branch .LBB0_1542

.LBB0_1555:
	s_or_b64 exec, exec, s[12:13]
	v_cvt_f32_u32_e32 v4, v1
	s_waitcnt vmcnt(0)
	v_readfirstlane_b32 s12, v3
	s_add_u32 s10, s94, 0x7500
	s_addc_u32 s11, s95, 0
	s_mov_b64 s[14:15], -1
	v_add_u32_e32 v2, s12, v2
	v_add_u32_e32 v2, 1, v2
	v_mul_u32_u24_e32 v1, 18, v1
	v_mov_b32_e32 v4, 17
	v_cmp_ne_u32_e32 vcc, v2, v1
	v_mov_b64_e32 v[2:3], s[10:11]
	s_and_saveexec_b64 s[12:13], vcc
	s_cbranch_execz .LBB0_1567
	v_mov_b32_e32 v1, 0
	global_load_dword v2, v1, s[100:101] sc1
	s_mov_b64 s[16:17], 0
	s_waitcnt vmcnt(0)
	v_cmp_lt_u32_e32 vcc, v2, v18
	s_and_saveexec_b64 s[14:15], vcc
	s_cbranch_execz .LBB0_1566
	s_mov_b32 s28, 1
	s_branch .LBB0_1559

.LBB0_1632:
	s_or_b64 exec, exec, s[12:13]
	v_cvt_f32_u32_e32 v5, v3
	s_waitcnt vmcnt(0)
	v_readfirstlane_b32 s10, v4
	buffer_inv sc1
	s_add_u32 s8, s8, 0x2400
	s_addc_u32 s9, s9, 0
	v_add_u32_e32 v6, s10, v2
	v_add_u32_e32 v4, 1, v6
	v_mul_u32_u24_e32 v3, 19, v3
	v_mov_b32_e32 v2, 18
	v_cmp_ne_u32_e32 vcc, v4, v3
	s_and_saveexec_b64 s[10:11], vcc
	s_xor_b64 s[10:11], exec, s[10:11]
	s_cbranch_execz .LBB0_1646
	s_waitcnt lgkmcnt(0)
	v_mov_b32_e32 v1, 0
	global_load_dword v3, v1, s[8:9] sc1
	s_waitcnt vmcnt(0)
	v_cmp_eq_u32_e32 vcc, v3, v2
	s_and_saveexec_b64 s[12:13], vcc
	s_cbranch_execz .LBB0_1645
	s_mov_b32 s26, 1
	s_mov_b64 s[14:15], 0
	s_branch .LBB0_1636

.LBB0_1649:
	s_or_b64 exec, exec, s[12:13]
	v_cvt_f32_u32_e32 v4, v1
	s_waitcnt vmcnt(0)
	v_readfirstlane_b32 s12, v3
	s_add_u32 s10, s94, 0x7500
	s_addc_u32 s11, s95, 0
	s_mov_b64 s[14:15], -1
	v_add_u32_e32 v2, s12, v2
	v_add_u32_e32 v2, 1, v2
	v_mul_u32_u24_e32 v1, 19, v1
	v_mov_b32_e32 v4, 18
	v_cmp_ne_u32_e32 vcc, v2, v1
	v_mov_b64_e32 v[2:3], s[10:11]
	s_and_saveexec_b64 s[12:13], vcc
	s_cbranch_execz .LBB0_1661
	v_mov_b32_e32 v1, 0
	global_load_dword v2, v1, s[100:101] sc1
	s_mov_b64 s[16:17], 0
	s_waitcnt vmcnt(0)
	v_cmp_lt_u32_e32 vcc, v2, v18
	s_and_saveexec_b64 s[14:15], vcc
	s_cbranch_execz .LBB0_1660
	s_mov_b32 s28, 1
	s_branch .LBB0_1653

.LBB0_1729:
	s_or_b64 exec, exec, s[12:13]
	v_cvt_f32_u32_e32 v5, v3
	s_waitcnt vmcnt(0)
	v_readfirstlane_b32 s10, v4
	buffer_inv sc1
	s_add_u32 s8, s8, 0x2400
	s_addc_u32 s9, s9, 0
	v_add_u32_e32 v6, s10, v2
	v_add_u32_e32 v4, 1, v6
	v_mul_u32_u24_e32 v3, 20, v3
	v_mov_b32_e32 v2, 19
	v_cmp_ne_u32_e32 vcc, v4, v3
	s_and_saveexec_b64 s[10:11], vcc
	s_xor_b64 s[10:11], exec, s[10:11]
	s_cbranch_execz .LBB0_1743
	s_waitcnt lgkmcnt(0)
	v_mov_b32_e32 v1, 0
	global_load_dword v3, v1, s[8:9] sc1
	s_waitcnt vmcnt(0)
	v_cmp_eq_u32_e32 vcc, v3, v2
	s_and_saveexec_b64 s[12:13], vcc
	s_cbranch_execz .LBB0_1742
	s_mov_b32 s26, 1
	s_mov_b64 s[14:15], 0
	s_branch .LBB0_1733

.LBB0_1746:
	s_or_b64 exec, exec, s[12:13]
	v_cvt_f32_u32_e32 v4, v1
	s_waitcnt vmcnt(0)
	v_readfirstlane_b32 s12, v3
	s_add_u32 s10, s94, 0x7500
	s_addc_u32 s11, s95, 0
	s_mov_b64 s[14:15], -1
	v_add_u32_e32 v2, s12, v2
	v_add_u32_e32 v2, 1, v2
	v_mul_u32_u24_e32 v1, 20, v1
	v_mov_b32_e32 v4, 19
	v_cmp_ne_u32_e32 vcc, v2, v1
	v_mov_b64_e32 v[2:3], s[10:11]
	s_and_saveexec_b64 s[12:13], vcc
	s_cbranch_execz .LBB0_1758
	v_mov_b32_e32 v1, 0
	global_load_dword v2, v1, s[100:101] sc1
	s_mov_b64 s[16:17], 0
	s_waitcnt vmcnt(0)
	v_cmp_lt_u32_e32 vcc, v2, v18
	s_and_saveexec_b64 s[14:15], vcc
	s_cbranch_execz .LBB0_1757
	s_mov_b32 s28, 1
	s_branch .LBB0_1750

.LBB0_1809:
	s_or_b64 exec, exec, s[12:13]
	v_cvt_f32_u32_e32 v5, v3
	s_waitcnt vmcnt(0)
	v_readfirstlane_b32 s10, v4
	buffer_inv sc1
	s_add_u32 s8, s8, 0x2400
	s_addc_u32 s9, s9, 0
	v_add_u32_e32 v6, s10, v2
	v_add_u32_e32 v4, 1, v6
	v_mul_u32_u24_e32 v3, 21, v3
	v_mov_b32_e32 v2, 20
	v_cmp_ne_u32_e32 vcc, v4, v3
	s_and_saveexec_b64 s[10:11], vcc
	s_xor_b64 s[10:11], exec, s[10:11]
	s_cbranch_execz .LBB0_1823
	s_waitcnt lgkmcnt(0)
	v_mov_b32_e32 v1, 0
	global_load_dword v3, v1, s[8:9] sc1
	s_waitcnt vmcnt(0)
	v_cmp_eq_u32_e32 vcc, v3, v2
	s_and_saveexec_b64 s[12:13], vcc
	s_cbranch_execz .LBB0_1822
	s_mov_b32 s26, 1
	s_mov_b64 s[14:15], 0
	s_branch .LBB0_1813

.LBB0_1826:
	s_or_b64 exec, exec, s[12:13]
	v_cvt_f32_u32_e32 v4, v1
	s_waitcnt vmcnt(0)
	v_readfirstlane_b32 s12, v3
	s_add_u32 s10, s94, 0x7500
	s_addc_u32 s11, s95, 0
	s_mov_b64 s[14:15], -1
	v_add_u32_e32 v2, s12, v2
	v_add_u32_e32 v2, 1, v2
	v_mul_u32_u24_e32 v1, 21, v1
	v_mov_b32_e32 v4, 20
	v_cmp_ne_u32_e32 vcc, v2, v1
	v_mov_b64_e32 v[2:3], s[10:11]
	s_and_saveexec_b64 s[12:13], vcc
	s_cbranch_execz .LBB0_1838
	v_mov_b32_e32 v1, 0
	global_load_dword v2, v1, s[100:101] sc1
	s_mov_b64 s[16:17], 0
	s_waitcnt vmcnt(0)
	v_cmp_lt_u32_e32 vcc, v2, v18
	s_and_saveexec_b64 s[14:15], vcc
	s_cbranch_execz .LBB0_1837
	s_mov_b32 s28, 1
	s_branch .LBB0_1830

.LBB0_1903:
	s_or_b64 exec, exec, s[12:13]
	v_cvt_f32_u32_e32 v5, v3
	s_waitcnt vmcnt(0)
	v_readfirstlane_b32 s10, v4
	buffer_inv sc1
	s_add_u32 s8, s8, 0x2400
	s_addc_u32 s9, s9, 0
	v_add_u32_e32 v6, s10, v2
	v_add_u32_e32 v4, 1, v6
	v_mul_u32_u24_e32 v3, 22, v3
	v_mov_b32_e32 v2, 21
	v_cmp_ne_u32_e32 vcc, v4, v3
	s_and_saveexec_b64 s[10:11], vcc
	s_xor_b64 s[10:11], exec, s[10:11]
	s_cbranch_execz .LBB0_1917
	s_waitcnt lgkmcnt(0)
	v_mov_b32_e32 v1, 0
	global_load_dword v3, v1, s[8:9] sc1
	s_waitcnt vmcnt(0)
	v_cmp_eq_u32_e32 vcc, v3, v2
	s_and_saveexec_b64 s[12:13], vcc
	s_cbranch_execz .LBB0_1916
	s_mov_b32 s26, 1
	s_mov_b64 s[14:15], 0
	s_branch .LBB0_1907

.LBB0_1920:
	s_or_b64 exec, exec, s[12:13]
	v_cvt_f32_u32_e32 v4, v1
	s_waitcnt vmcnt(0)
	v_readfirstlane_b32 s12, v3
	s_add_u32 s10, s94, 0x7500
	s_addc_u32 s11, s95, 0
	s_mov_b64 s[14:15], -1
	v_add_u32_e32 v2, s12, v2
	v_add_u32_e32 v2, 1, v2
	v_mul_u32_u24_e32 v1, 22, v1
	v_mov_b32_e32 v4, 21
	v_cmp_ne_u32_e32 vcc, v2, v1
	v_mov_b64_e32 v[2:3], s[10:11]
	s_and_saveexec_b64 s[12:13], vcc
	s_cbranch_execz .LBB0_1932
	v_mov_b32_e32 v1, 0
	global_load_dword v2, v1, s[100:101] sc1
	s_mov_b64 s[16:17], 0
	s_waitcnt vmcnt(0)
	v_cmp_lt_u32_e32 vcc, v2, v18
	s_and_saveexec_b64 s[14:15], vcc
	s_cbranch_execz .LBB0_1931
	s_mov_b32 s28, 1
	s_branch .LBB0_1924

.LBB0_2000:
	s_or_b64 exec, exec, s[12:13]
	v_cvt_f32_u32_e32 v5, v3
	s_waitcnt vmcnt(0)
	v_readfirstlane_b32 s10, v4
	buffer_inv sc1
	s_add_u32 s8, s8, 0x2400
	s_addc_u32 s9, s9, 0
	v_add_u32_e32 v6, s10, v2
	v_add_u32_e32 v4, 1, v6
	v_mul_u32_u24_e32 v3, 23, v3
	v_mov_b32_e32 v2, 22
	v_cmp_ne_u32_e32 vcc, v4, v3
	s_and_saveexec_b64 s[10:11], vcc
	s_xor_b64 s[10:11], exec, s[10:11]
	s_cbranch_execz .LBB0_2014
	s_waitcnt lgkmcnt(0)
	v_mov_b32_e32 v1, 0
	global_load_dword v3, v1, s[8:9] sc1
	s_waitcnt vmcnt(0)
	v_cmp_eq_u32_e32 vcc, v3, v2
	s_and_saveexec_b64 s[12:13], vcc
	s_cbranch_execz .LBB0_2013
	s_mov_b32 s26, 1
	s_mov_b64 s[14:15], 0
	s_branch .LBB0_2004

.LBB0_2017:
	s_or_b64 exec, exec, s[12:13]
	v_cvt_f32_u32_e32 v4, v1
	s_waitcnt vmcnt(0)
	v_readfirstlane_b32 s12, v3
	s_add_u32 s10, s94, 0x7500
	s_addc_u32 s11, s95, 0
	s_mov_b64 s[14:15], -1
	v_add_u32_e32 v2, s12, v2
	v_add_u32_e32 v2, 1, v2
	v_mul_u32_u24_e32 v1, 23, v1
	v_mov_b32_e32 v4, 22
	v_cmp_ne_u32_e32 vcc, v2, v1
	v_mov_b64_e32 v[2:3], s[10:11]
	s_and_saveexec_b64 s[12:13], vcc
	s_cbranch_execz .LBB0_2029
	v_mov_b32_e32 v1, 0
	global_load_dword v2, v1, s[100:101] sc1
	s_mov_b64 s[16:17], 0
	s_waitcnt vmcnt(0)
	v_cmp_lt_u32_e32 vcc, v2, v18
	s_and_saveexec_b64 s[14:15], vcc
	s_cbranch_execz .LBB0_2028
	s_mov_b32 s28, 1
	s_branch .LBB0_2021

.LBB0_2072:
	s_or_b64 exec, exec, s[12:13]
	v_cvt_f32_u32_e32 v5, v3
	s_waitcnt vmcnt(0)
	v_readfirstlane_b32 s10, v4
	buffer_inv sc1
	s_add_u32 s8, s8, 0x2400
	s_addc_u32 s9, s9, 0
	v_add_u32_e32 v6, s10, v2
	v_add_u32_e32 v4, 1, v6
	v_mul_u32_u24_e32 v3, 24, v3
	v_mov_b32_e32 v2, 23
	v_cmp_ne_u32_e32 vcc, v4, v3
	s_and_saveexec_b64 s[10:11], vcc
	s_xor_b64 s[10:11], exec, s[10:11]
	s_cbranch_execz .LBB0_2086
	s_waitcnt lgkmcnt(0)
	v_mov_b32_e32 v1, 0
	global_load_dword v3, v1, s[8:9] sc1
	s_waitcnt vmcnt(0)
	v_cmp_eq_u32_e32 vcc, v3, v2
	s_and_saveexec_b64 s[12:13], vcc
	s_cbranch_execz .LBB0_2085
	s_mov_b32 s26, 1
	s_mov_b64 s[14:15], 0
	s_branch .LBB0_2076

.LBB0_2089:
	s_or_b64 exec, exec, s[12:13]
	v_cvt_f32_u32_e32 v4, v1
	s_waitcnt vmcnt(0)
	v_readfirstlane_b32 s12, v3
	s_add_u32 s10, s94, 0x7500
	s_addc_u32 s11, s95, 0
	s_mov_b64 s[14:15], -1
	v_add_u32_e32 v2, s12, v2
	v_add_u32_e32 v2, 1, v2
	v_mul_u32_u24_e32 v1, 24, v1
	v_mov_b32_e32 v4, 23
	v_cmp_ne_u32_e32 vcc, v2, v1
	v_mov_b64_e32 v[2:3], s[10:11]
	s_and_saveexec_b64 s[12:13], vcc
	s_cbranch_execz .LBB0_2101
	v_mov_b32_e32 v1, 0
	global_load_dword v2, v1, s[100:101] sc1
	s_mov_b64 s[16:17], 0
	s_waitcnt vmcnt(0)
	v_cmp_lt_u32_e32 vcc, v2, v18
	s_and_saveexec_b64 s[14:15], vcc
	s_cbranch_execz .LBB0_2100
	s_mov_b32 s28, 1
	s_branch .LBB0_2093

.LBB0_2252:
	s_or_b64 exec, exec, s[10:11]
	v_cvt_f32_u32_e32 v5, v3
	s_waitcnt vmcnt(0)
	v_readfirstlane_b32 s8, v4
	buffer_inv sc1
	s_add_u32 s6, s6, 0x2400
	s_addc_u32 s7, s7, 0
	v_add_u32_e32 v6, s8, v2
	v_add_u32_e32 v4, 1, v6
	v_mul_u32_u24_e32 v3, 25, v3
	v_mov_b32_e32 v2, 24
	v_cmp_ne_u32_e32 vcc, v4, v3
	s_and_saveexec_b64 s[8:9], vcc
	s_xor_b64 s[8:9], exec, s[8:9]
	s_cbranch_execz .LBB0_2266
	s_waitcnt lgkmcnt(0)
	v_mov_b32_e32 v1, 0
	global_load_dword v3, v1, s[6:7] sc1
	s_waitcnt vmcnt(0)
	v_cmp_eq_u32_e32 vcc, v3, v2
	s_and_saveexec_b64 s[10:11], vcc
	s_cbranch_execz .LBB0_2265
	s_mov_b32 s24, 1
	s_mov_b64 s[12:13], 0
	s_branch .LBB0_2256

.LBB0_2269:
	s_or_b64 exec, exec, s[10:11]
	v_cvt_f32_u32_e32 v4, v1
	s_waitcnt vmcnt(0)
	v_readfirstlane_b32 s10, v3
	s_add_u32 s8, s94, 0x7500
	s_addc_u32 s9, s95, 0
	s_mov_b64 s[12:13], -1
	v_add_u32_e32 v2, s10, v2
	v_add_u32_e32 v2, 1, v2
	v_mul_u32_u24_e32 v1, 25, v1
	v_mov_b32_e32 v4, 24
	v_cmp_ne_u32_e32 vcc, v2, v1
	v_mov_b64_e32 v[2:3], s[8:9]
	s_and_saveexec_b64 s[10:11], vcc
	s_cbranch_execz .LBB0_2281
	v_mov_b32_e32 v1, 0
	global_load_dword v2, v1, s[100:101] sc1
	s_mov_b64 s[14:15], 0
	s_waitcnt vmcnt(0)
	v_cmp_lt_u32_e32 vcc, v2, v18
	s_and_saveexec_b64 s[12:13], vcc
	s_cbranch_execz .LBB0_2280
	s_mov_b32 s26, 1
	s_branch .LBB0_2273

.LBB0_2333:
	s_or_b64 exec, exec, s[10:11]
	v_cvt_f32_u32_e32 v5, v3
	s_waitcnt vmcnt(0)
	v_readfirstlane_b32 s8, v4
	buffer_inv sc1
	s_add_u32 s6, s6, 0x2400
	s_addc_u32 s7, s7, 0
	v_add_u32_e32 v6, s8, v2
	v_add_u32_e32 v4, 1, v6
	v_mul_u32_u24_e32 v3, 26, v3
	v_mov_b32_e32 v2, 25
	v_cmp_ne_u32_e32 vcc, v4, v3
	s_and_saveexec_b64 s[8:9], vcc
	s_xor_b64 s[8:9], exec, s[8:9]
	s_cbranch_execz .LBB0_2347
	s_waitcnt lgkmcnt(0)
	v_mov_b32_e32 v1, 0
	global_load_dword v3, v1, s[6:7] sc1
	s_waitcnt vmcnt(0)
	v_cmp_eq_u32_e32 vcc, v3, v2
	s_and_saveexec_b64 s[10:11], vcc
	s_cbranch_execz .LBB0_2346
	s_mov_b32 s24, 1
	s_mov_b64 s[12:13], 0
	s_branch .LBB0_2337

.LBB0_2350:
	s_or_b64 exec, exec, s[10:11]
	v_cvt_f32_u32_e32 v4, v1
	s_waitcnt vmcnt(0)
	v_readfirstlane_b32 s10, v3
	s_add_u32 s8, s94, 0x7500
	s_addc_u32 s9, s95, 0
	s_mov_b64 s[12:13], -1
	v_add_u32_e32 v2, s10, v2
	v_add_u32_e32 v2, 1, v2
	v_mul_u32_u24_e32 v1, 26, v1
	v_mov_b32_e32 v4, 25
	v_cmp_ne_u32_e32 vcc, v2, v1
	v_mov_b64_e32 v[2:3], s[8:9]
	s_and_saveexec_b64 s[10:11], vcc
	s_cbranch_execz .LBB0_2362
	v_mov_b32_e32 v1, 0
	global_load_dword v2, v1, s[100:101] sc1
	s_mov_b64 s[14:15], 0
	s_waitcnt vmcnt(0)
	v_cmp_lt_u32_e32 vcc, v2, v18
	s_and_saveexec_b64 s[12:13], vcc
	s_cbranch_execz .LBB0_2361
	s_mov_b32 s26, 1
	s_branch .LBB0_2354

.LBB0_2413:
	s_or_b64 exec, exec, s[10:11]
	v_cvt_f32_u32_e32 v5, v3
	s_waitcnt vmcnt(0)
	v_readfirstlane_b32 s8, v4
	buffer_inv sc1
	s_add_u32 s6, s6, 0x2400
	s_addc_u32 s7, s7, 0
	v_add_u32_e32 v6, s8, v2
	v_add_u32_e32 v4, 1, v6
	v_mul_u32_u24_e32 v3, 27, v3
	v_mov_b32_e32 v2, 26
	v_cmp_ne_u32_e32 vcc, v4, v3
	s_and_saveexec_b64 s[8:9], vcc
	s_xor_b64 s[8:9], exec, s[8:9]
	s_cbranch_execz .LBB0_2427
	s_waitcnt lgkmcnt(0)
	v_mov_b32_e32 v1, 0
	global_load_dword v3, v1, s[6:7] sc1
	s_waitcnt vmcnt(0)
	v_cmp_eq_u32_e32 vcc, v3, v2
	s_and_saveexec_b64 s[10:11], vcc
	s_cbranch_execz .LBB0_2426
	s_mov_b32 s24, 1
	s_mov_b64 s[12:13], 0
	s_branch .LBB0_2417

.LBB0_2430:
	s_or_b64 exec, exec, s[10:11]
	v_cvt_f32_u32_e32 v4, v1
	s_waitcnt vmcnt(0)
	v_readfirstlane_b32 s10, v3
	s_add_u32 s8, s94, 0x7500
	s_addc_u32 s9, s95, 0
	s_mov_b64 s[12:13], -1
	v_add_u32_e32 v2, s10, v2
	v_add_u32_e32 v2, 1, v2
	v_mul_u32_u24_e32 v1, 27, v1
	v_mov_b32_e32 v4, 26
	v_cmp_ne_u32_e32 vcc, v2, v1
	v_mov_b64_e32 v[2:3], s[8:9]
	s_and_saveexec_b64 s[10:11], vcc
	s_cbranch_execz .LBB0_2442
	v_mov_b32_e32 v1, 0
	global_load_dword v2, v1, s[100:101] sc1
	s_mov_b64 s[14:15], 0
	s_waitcnt vmcnt(0)
	v_cmp_lt_u32_e32 vcc, v2, v18
	s_and_saveexec_b64 s[12:13], vcc
	s_cbranch_execz .LBB0_2441
	s_mov_b32 s26, 1
	s_branch .LBB0_2434

.LBB0_2507:
	s_or_b64 exec, exec, s[10:11]
	v_cvt_f32_u32_e32 v5, v3
	s_waitcnt vmcnt(0)
	v_readfirstlane_b32 s8, v4
	buffer_inv sc1
	s_add_u32 s6, s6, 0x2400
	s_addc_u32 s7, s7, 0
	v_add_u32_e32 v6, s8, v2
	v_add_u32_e32 v4, 1, v6
	v_mul_u32_u24_e32 v3, 28, v3
	v_mov_b32_e32 v2, 27
	v_cmp_ne_u32_e32 vcc, v4, v3
	s_and_saveexec_b64 s[8:9], vcc
	s_xor_b64 s[8:9], exec, s[8:9]
	s_cbranch_execz .LBB0_2521
	s_waitcnt lgkmcnt(0)
	v_mov_b32_e32 v1, 0
	global_load_dword v3, v1, s[6:7] sc1
	s_waitcnt vmcnt(0)
	v_cmp_eq_u32_e32 vcc, v3, v2
	s_and_saveexec_b64 s[10:11], vcc
	s_cbranch_execz .LBB0_2520
	s_mov_b32 s24, 1
	s_mov_b64 s[12:13], 0
	s_branch .LBB0_2511

.LBB0_2524:
	s_or_b64 exec, exec, s[10:11]
	v_cvt_f32_u32_e32 v4, v1
	s_waitcnt vmcnt(0)
	v_readfirstlane_b32 s10, v3
	s_add_u32 s8, s94, 0x7500
	s_addc_u32 s9, s95, 0
	s_mov_b64 s[12:13], -1
	v_add_u32_e32 v2, s10, v2
	v_add_u32_e32 v2, 1, v2
	v_mul_u32_u24_e32 v1, 28, v1
	v_mov_b32_e32 v4, 27
	v_cmp_ne_u32_e32 vcc, v2, v1
	v_mov_b64_e32 v[2:3], s[8:9]
	s_and_saveexec_b64 s[10:11], vcc
	s_cbranch_execz .LBB0_2536
	v_mov_b32_e32 v1, 0
	global_load_dword v2, v1, s[100:101] sc1
	s_mov_b64 s[14:15], 0
	s_waitcnt vmcnt(0)
	v_cmp_lt_u32_e32 vcc, v2, v18
	s_and_saveexec_b64 s[12:13], vcc
	s_cbranch_execz .LBB0_2535
	s_mov_b32 s26, 1
	s_branch .LBB0_2528

.LBB0_2604:
	s_or_b64 exec, exec, s[10:11]
	v_cvt_f32_u32_e32 v5, v3
	s_waitcnt vmcnt(0)
	v_readfirstlane_b32 s8, v4
	buffer_inv sc1
	s_add_u32 s6, s6, 0x2400
	s_addc_u32 s7, s7, 0
	v_add_u32_e32 v6, s8, v2
	v_add_u32_e32 v4, 1, v6
	v_mul_u32_u24_e32 v3, 29, v3
	v_mov_b32_e32 v2, 28
	v_cmp_ne_u32_e32 vcc, v4, v3
	s_and_saveexec_b64 s[8:9], vcc
	s_xor_b64 s[8:9], exec, s[8:9]
	s_cbranch_execz .LBB0_2618
	s_waitcnt lgkmcnt(0)
	v_mov_b32_e32 v1, 0
	global_load_dword v3, v1, s[6:7] sc1
	s_waitcnt vmcnt(0)
	v_cmp_eq_u32_e32 vcc, v3, v2
	s_and_saveexec_b64 s[10:11], vcc
	s_cbranch_execz .LBB0_2617
	s_mov_b32 s24, 1
	s_mov_b64 s[12:13], 0
	s_branch .LBB0_2608

.LBB0_2621:
	s_or_b64 exec, exec, s[10:11]
	v_cvt_f32_u32_e32 v4, v1
	s_waitcnt vmcnt(0)
	v_readfirstlane_b32 s10, v3
	s_add_u32 s8, s94, 0x7500
	s_addc_u32 s9, s95, 0
	s_mov_b64 s[12:13], -1
	v_add_u32_e32 v2, s10, v2
	v_add_u32_e32 v2, 1, v2
	v_mul_u32_u24_e32 v1, 29, v1
	v_mov_b32_e32 v4, 28
	v_cmp_ne_u32_e32 vcc, v2, v1
	v_mov_b64_e32 v[2:3], s[8:9]
	s_and_saveexec_b64 s[10:11], vcc
	s_cbranch_execz .LBB0_2633
	v_mov_b32_e32 v1, 0
	global_load_dword v2, v1, s[100:101] sc1
	s_mov_b64 s[14:15], 0
	s_waitcnt vmcnt(0)
	v_cmp_lt_u32_e32 vcc, v2, v18
	s_and_saveexec_b64 s[12:13], vcc
	s_cbranch_execz .LBB0_2632
	s_mov_b32 s26, 1
	s_branch .LBB0_2625

.LBB0_2684:
	s_or_b64 exec, exec, s[10:11]
	v_cvt_f32_u32_e32 v5, v3
	s_waitcnt vmcnt(0)
	v_readfirstlane_b32 s8, v4
	buffer_inv sc1
	s_add_u32 s6, s6, 0x2400
	s_addc_u32 s7, s7, 0
	v_add_u32_e32 v6, s8, v2
	v_add_u32_e32 v4, 1, v6
	v_mul_u32_u24_e32 v3, 30, v3
	v_mov_b32_e32 v2, 29
	v_cmp_ne_u32_e32 vcc, v4, v3
	s_and_saveexec_b64 s[8:9], vcc
	s_xor_b64 s[8:9], exec, s[8:9]
	s_cbranch_execz .LBB0_2698
	s_waitcnt lgkmcnt(0)
	v_mov_b32_e32 v1, 0
	global_load_dword v3, v1, s[6:7] sc1
	s_waitcnt vmcnt(0)
	v_cmp_eq_u32_e32 vcc, v3, v2
	s_and_saveexec_b64 s[10:11], vcc
	s_cbranch_execz .LBB0_2697
	s_mov_b32 s24, 1
	s_mov_b64 s[12:13], 0
	s_branch .LBB0_2688

.LBB0_2701:
	s_or_b64 exec, exec, s[10:11]
	v_cvt_f32_u32_e32 v4, v1
	s_waitcnt vmcnt(0)
	v_readfirstlane_b32 s10, v3
	s_add_u32 s8, s94, 0x7500
	s_addc_u32 s9, s95, 0
	s_mov_b64 s[12:13], -1
	v_add_u32_e32 v2, s10, v2
	v_add_u32_e32 v2, 1, v2
	v_mul_u32_u24_e32 v1, 30, v1
	v_mov_b32_e32 v4, 29
	v_cmp_ne_u32_e32 vcc, v2, v1
	v_mov_b64_e32 v[2:3], s[8:9]
	s_and_saveexec_b64 s[10:11], vcc
	s_cbranch_execz .LBB0_2713
	v_mov_b32_e32 v1, 0
	global_load_dword v2, v1, s[100:101] sc1
	s_mov_b64 s[14:15], 0
	s_waitcnt vmcnt(0)
	v_cmp_lt_u32_e32 vcc, v2, v18
	s_and_saveexec_b64 s[12:13], vcc
	s_cbranch_execz .LBB0_2712
	s_mov_b32 s26, 1
	s_branch .LBB0_2705

.LBB0_2778:
	s_or_b64 exec, exec, s[10:11]
	v_cvt_f32_u32_e32 v5, v3
	s_waitcnt vmcnt(0)
	v_readfirstlane_b32 s8, v4
	buffer_inv sc1
	s_add_u32 s6, s6, 0x2400
	s_addc_u32 s7, s7, 0
	v_add_u32_e32 v6, s8, v2
	v_add_u32_e32 v4, 1, v6
	v_mul_u32_u24_e32 v3, 31, v3
	v_mov_b32_e32 v2, 30
	v_cmp_ne_u32_e32 vcc, v4, v3
	s_and_saveexec_b64 s[8:9], vcc
	s_xor_b64 s[8:9], exec, s[8:9]
	s_cbranch_execz .LBB0_2792
	s_waitcnt lgkmcnt(0)
	v_mov_b32_e32 v1, 0
	global_load_dword v3, v1, s[6:7] sc1
	s_waitcnt vmcnt(0)
	v_cmp_eq_u32_e32 vcc, v3, v2
	s_and_saveexec_b64 s[10:11], vcc
	s_cbranch_execz .LBB0_2791
	s_mov_b32 s24, 1
	s_mov_b64 s[12:13], 0
	s_branch .LBB0_2782

.LBB0_2795:
	s_or_b64 exec, exec, s[10:11]
	v_cvt_f32_u32_e32 v4, v1
	s_waitcnt vmcnt(0)
	v_readfirstlane_b32 s10, v3
	s_add_u32 s8, s94, 0x7500
	s_addc_u32 s9, s95, 0
	s_mov_b64 s[12:13], -1
	v_add_u32_e32 v2, s10, v2
	v_add_u32_e32 v2, 1, v2
	v_mul_u32_u24_e32 v1, 31, v1
	v_mov_b32_e32 v4, 30
	v_cmp_ne_u32_e32 vcc, v2, v1
	v_mov_b64_e32 v[2:3], s[8:9]
	s_and_saveexec_b64 s[10:11], vcc
	s_cbranch_execz .LBB0_2807
	v_mov_b32_e32 v1, 0
	global_load_dword v2, v1, s[100:101] sc1
	s_mov_b64 s[14:15], 0
	s_waitcnt vmcnt(0)
	v_cmp_lt_u32_e32 vcc, v2, v18
	s_and_saveexec_b64 s[12:13], vcc
	s_cbranch_execz .LBB0_2806
	s_mov_b32 s26, 1
	s_branch .LBB0_2799

.LBB0_2875:
	s_or_b64 exec, exec, s[10:11]
	v_cvt_f32_u32_e32 v5, v3
	s_waitcnt vmcnt(0)
	v_readfirstlane_b32 s8, v4
	buffer_inv sc1
	s_add_u32 s6, s6, 0x2400
	s_addc_u32 s7, s7, 0
	v_add_u32_e32 v6, s8, v2
	v_add_u32_e32 v4, 1, v6
	v_mul_u32_u24_e32 v3, 32, v3
	v_mov_b32_e32 v2, 31
	v_cmp_ne_u32_e32 vcc, v4, v3
	s_and_saveexec_b64 s[8:9], vcc
	s_xor_b64 s[8:9], exec, s[8:9]
	s_cbranch_execz .LBB0_2889
	s_waitcnt lgkmcnt(0)
	v_mov_b32_e32 v1, 0
	global_load_dword v3, v1, s[6:7] sc1
	s_waitcnt vmcnt(0)
	v_cmp_eq_u32_e32 vcc, v3, v2
	s_and_saveexec_b64 s[10:11], vcc
	s_cbranch_execz .LBB0_2888
	s_mov_b32 s24, 1
	s_mov_b64 s[12:13], 0
	s_branch .LBB0_2879

.LBB0_2892:
	s_or_b64 exec, exec, s[10:11]
	v_cvt_f32_u32_e32 v4, v1
	s_waitcnt vmcnt(0)
	v_readfirstlane_b32 s10, v3
	s_add_u32 s8, s94, 0x7500
	s_addc_u32 s9, s95, 0
	s_mov_b64 s[12:13], -1
	v_add_u32_e32 v2, s10, v2
	v_add_u32_e32 v2, 1, v2
	v_mul_u32_u24_e32 v1, 32, v1
	v_mov_b32_e32 v4, 31
	v_cmp_ne_u32_e32 vcc, v2, v1
	v_mov_b64_e32 v[2:3], s[8:9]
	s_and_saveexec_b64 s[10:11], vcc
	s_cbranch_execz .LBB0_2904
	v_mov_b32_e32 v1, 0
	global_load_dword v2, v1, s[100:101] sc1
	s_mov_b64 s[14:15], 0
	s_waitcnt vmcnt(0)
	v_cmp_lt_u32_e32 vcc, v2, v18
	s_and_saveexec_b64 s[12:13], vcc
	s_cbranch_execz .LBB0_2903
	s_mov_b32 s26, 1
	s_branch .LBB0_2896

.LBB0_2947:
	s_or_b64 exec, exec, s[10:11]
	v_cvt_f32_u32_e32 v5, v3
	s_waitcnt vmcnt(0)
	v_readfirstlane_b32 s8, v4
	buffer_inv sc1
	s_add_u32 s6, s6, 0x2400
	s_addc_u32 s7, s7, 0
	v_add_u32_e32 v6, s8, v2
	v_add_u32_e32 v4, 1, v6
	v_mul_u32_u24_e32 v3, 33, v3
	v_mov_b32_e32 v2, 32
	v_cmp_ne_u32_e32 vcc, v4, v3
	s_and_saveexec_b64 s[8:9], vcc
	s_xor_b64 s[8:9], exec, s[8:9]
	s_cbranch_execz .LBB0_2961
	s_waitcnt lgkmcnt(0)
	v_mov_b32_e32 v1, 0
	global_load_dword v3, v1, s[6:7] sc1
	s_waitcnt vmcnt(0)
	v_cmp_eq_u32_e32 vcc, v3, v2
	s_and_saveexec_b64 s[10:11], vcc
	s_cbranch_execz .LBB0_2960
	s_mov_b32 s24, 1
	s_mov_b64 s[12:13], 0
	s_branch .LBB0_2951

.LBB0_2964:
	s_or_b64 exec, exec, s[10:11]
	v_cvt_f32_u32_e32 v4, v1
	s_waitcnt vmcnt(0)
	v_readfirstlane_b32 s10, v3
	s_add_u32 s8, s94, 0x7500
	s_addc_u32 s9, s95, 0
	s_mov_b64 s[12:13], -1
	v_add_u32_e32 v2, s10, v2
	v_add_u32_e32 v2, 1, v2
	v_mul_u32_u24_e32 v1, 33, v1
	v_mov_b32_e32 v4, 32
	v_cmp_ne_u32_e32 vcc, v2, v1
	v_mov_b64_e32 v[2:3], s[8:9]
	s_and_saveexec_b64 s[10:11], vcc
	s_cbranch_execz .LBB0_2976
	v_mov_b32_e32 v1, 0
	global_load_dword v2, v1, s[100:101] sc1
	s_mov_b64 s[14:15], 0
	s_waitcnt vmcnt(0)
	v_cmp_lt_u32_e32 vcc, v2, v18
	s_and_saveexec_b64 s[12:13], vcc
	s_cbranch_execz .LBB0_2975
	s_mov_b32 s26, 1
	s_branch .LBB0_2968

.LBB0_3045:
	s_or_b64 exec, exec, s[10:11]
	v_cvt_f32_u32_e32 v5, v3
	s_waitcnt vmcnt(0)
	v_readfirstlane_b32 s8, v4
	buffer_inv sc1
	s_add_u32 s6, s6, 0x2400
	s_addc_u32 s7, s7, 0
	v_add_u32_e32 v6, s8, v2
	v_add_u32_e32 v4, 1, v6
	v_mul_u32_u24_e32 v3, 34, v3
	v_mov_b32_e32 v2, 33
	v_cmp_ne_u32_e32 vcc, v4, v3
	s_and_saveexec_b64 s[8:9], vcc
	s_xor_b64 s[8:9], exec, s[8:9]
	s_cbranch_execz .LBB0_3059
	s_waitcnt lgkmcnt(0)
	v_mov_b32_e32 v1, 0
	global_load_dword v3, v1, s[6:7] sc1
	s_waitcnt vmcnt(0)
	v_cmp_eq_u32_e32 vcc, v3, v2
	s_and_saveexec_b64 s[10:11], vcc
	s_cbranch_execz .LBB0_3058
	s_mov_b32 s24, 1
	s_mov_b64 s[12:13], 0
	s_branch .LBB0_3049

.LBB0_3062:
	s_or_b64 exec, exec, s[10:11]
	v_cvt_f32_u32_e32 v4, v1
	s_waitcnt vmcnt(0)
	v_readfirstlane_b32 s10, v3
	s_add_u32 s8, s94, 0x7500
	s_addc_u32 s9, s95, 0
	s_mov_b64 s[12:13], -1
	v_add_u32_e32 v2, s10, v2
	v_add_u32_e32 v2, 1, v2
	v_mul_u32_u24_e32 v1, 34, v1
	v_mov_b32_e32 v4, 33
	v_cmp_ne_u32_e32 vcc, v2, v1
	v_mov_b64_e32 v[2:3], s[8:9]
	s_and_saveexec_b64 s[10:11], vcc
	s_cbranch_execz .LBB0_3074
	v_mov_b32_e32 v1, 0
	global_load_dword v2, v1, s[100:101] sc1
	s_mov_b64 s[14:15], 0
	s_waitcnt vmcnt(0)
	v_cmp_lt_u32_e32 vcc, v2, v18
	s_and_saveexec_b64 s[12:13], vcc
	s_cbranch_execz .LBB0_3073
	s_mov_b32 s26, 1
	s_branch .LBB0_3066

.LBB0_3108:
	s_or_b64 exec, exec, s[10:11]
	v_cvt_f32_u32_e32 v5, v3
	s_waitcnt vmcnt(0)
	v_readfirstlane_b32 s8, v4
	buffer_inv sc1
	s_add_u32 s6, s6, 0x2400
	s_addc_u32 s7, s7, 0
	v_add_u32_e32 v6, s8, v2
	v_add_u32_e32 v4, 1, v6
	v_mul_u32_u24_e32 v3, 35, v3
	v_mov_b32_e32 v2, 34
	v_cmp_ne_u32_e32 vcc, v4, v3
	s_and_saveexec_b64 s[8:9], vcc
	s_xor_b64 s[8:9], exec, s[8:9]
	s_cbranch_execz .LBB0_3122
	s_waitcnt lgkmcnt(0)
	v_mov_b32_e32 v1, 0
	global_load_dword v3, v1, s[6:7] sc1
	s_waitcnt vmcnt(0)
	v_cmp_eq_u32_e32 vcc, v3, v2
	s_and_saveexec_b64 s[10:11], vcc
	s_cbranch_execz .LBB0_3121
	s_mov_b32 s24, 1
	s_mov_b64 s[12:13], 0
	s_branch .LBB0_3112

.LBB0_3125:
	s_or_b64 exec, exec, s[10:11]
	v_cvt_f32_u32_e32 v4, v1
	s_waitcnt vmcnt(0)
	v_readfirstlane_b32 s10, v3
	s_add_u32 s8, s94, 0x7500
	s_addc_u32 s9, s95, 0
	s_mov_b64 s[12:13], -1
	v_add_u32_e32 v2, s10, v2
	v_add_u32_e32 v2, 1, v2
	v_mul_u32_u24_e32 v1, 35, v1
	v_mov_b32_e32 v4, 34
	v_cmp_ne_u32_e32 vcc, v2, v1
	v_mov_b64_e32 v[2:3], s[8:9]
	s_and_saveexec_b64 s[10:11], vcc
	s_cbranch_execz .LBB0_3137
	v_mov_b32_e32 v1, 0
	global_load_dword v2, v1, s[100:101] sc1
	s_mov_b64 s[14:15], 0
	s_waitcnt vmcnt(0)
	v_cmp_lt_u32_e32 vcc, v2, v18
	s_and_saveexec_b64 s[12:13], vcc
	s_cbranch_execz .LBB0_3136
	s_mov_b32 s26, 1
	s_branch .LBB0_3129

.LBB0_3169:
	s_or_b64 exec, exec, s[10:11]
	v_cvt_f32_u32_e32 v5, v3
	s_waitcnt vmcnt(0)
	v_readfirstlane_b32 s8, v4
	buffer_inv sc1
	s_add_u32 s6, s6, 0x2400
	s_addc_u32 s7, s7, 0
	v_add_u32_e32 v6, s8, v2
	v_add_u32_e32 v4, 1, v6
	v_mul_u32_u24_e32 v3, 36, v3
	v_mov_b32_e32 v2, 35
	v_cmp_ne_u32_e32 vcc, v4, v3
	s_and_saveexec_b64 s[8:9], vcc
	s_xor_b64 s[8:9], exec, s[8:9]
	s_cbranch_execz .LBB0_3183
	s_waitcnt lgkmcnt(0)
	v_mov_b32_e32 v1, 0
	global_load_dword v3, v1, s[6:7] sc1
	s_waitcnt vmcnt(0)
	v_cmp_eq_u32_e32 vcc, v3, v2
	s_and_saveexec_b64 s[10:11], vcc
	s_cbranch_execz .LBB0_3182
	s_mov_b32 s22, 1
	s_mov_b64 s[12:13], 0
	s_branch .LBB0_3173

.LBB0_3186:
	s_or_b64 exec, exec, s[10:11]
	v_cvt_f32_u32_e32 v4, v1
	s_waitcnt vmcnt(0)
	v_readfirstlane_b32 s10, v3
	s_add_u32 s8, s94, 0x7500
	s_addc_u32 s9, s95, 0
	s_mov_b64 s[12:13], -1
	v_add_u32_e32 v2, s10, v2
	v_add_u32_e32 v2, 1, v2
	v_mul_u32_u24_e32 v1, 36, v1
	v_mov_b32_e32 v4, 35
	v_cmp_ne_u32_e32 vcc, v2, v1
	v_mov_b64_e32 v[2:3], s[8:9]
	s_and_saveexec_b64 s[10:11], vcc
	s_cbranch_execz .LBB0_3198
	v_mov_b32_e32 v1, 0
	global_load_dword v2, v1, s[100:101] sc1
	s_mov_b64 s[14:15], 0
	s_waitcnt vmcnt(0)
	v_cmp_lt_u32_e32 vcc, v2, v18
	s_and_saveexec_b64 s[12:13], vcc
	s_cbranch_execz .LBB0_3197
	s_mov_b32 s24, 1
	s_branch .LBB0_3190

.LBB0_3250:
	s_or_b64 exec, exec, s[10:11]
	v_cvt_f32_u32_e32 v5, v3
	s_waitcnt vmcnt(0)
	v_readfirstlane_b32 s8, v4
	buffer_inv sc1
	s_add_u32 s6, s6, 0x2400
	s_addc_u32 s7, s7, 0
	v_add_u32_e32 v6, s8, v2
	v_add_u32_e32 v4, 1, v6
	v_mul_u32_u24_e32 v3, 37, v3
	v_mov_b32_e32 v2, 36
	v_cmp_ne_u32_e32 vcc, v4, v3
	s_and_saveexec_b64 s[8:9], vcc
	s_xor_b64 s[8:9], exec, s[8:9]
	s_cbranch_execz .LBB0_3264
	s_waitcnt lgkmcnt(0)
	v_mov_b32_e32 v1, 0
	global_load_dword v3, v1, s[6:7] sc1
	s_waitcnt vmcnt(0)
	v_cmp_eq_u32_e32 vcc, v3, v2
	s_and_saveexec_b64 s[10:11], vcc
	s_cbranch_execz .LBB0_3263
	s_mov_b32 s22, 1
	s_mov_b64 s[12:13], 0
	s_branch .LBB0_3254

.LBB0_3267:
	s_or_b64 exec, exec, s[10:11]
	v_cvt_f32_u32_e32 v4, v1
	s_waitcnt vmcnt(0)
	v_readfirstlane_b32 s10, v3
	s_add_u32 s8, s94, 0x7500
	s_addc_u32 s9, s95, 0
	s_mov_b64 s[12:13], -1
	v_add_u32_e32 v2, s10, v2
	v_add_u32_e32 v2, 1, v2
	v_mul_u32_u24_e32 v1, 37, v1
	v_mov_b32_e32 v4, 36
	v_cmp_ne_u32_e32 vcc, v2, v1
	v_mov_b64_e32 v[2:3], s[8:9]
	s_and_saveexec_b64 s[10:11], vcc
	s_cbranch_execz .LBB0_3279
	v_mov_b32_e32 v1, 0
	global_load_dword v2, v1, s[100:101] sc1
	s_mov_b64 s[14:15], 0
	s_waitcnt vmcnt(0)
	v_cmp_lt_u32_e32 vcc, v2, v18
	s_and_saveexec_b64 s[12:13], vcc
	s_cbranch_execz .LBB0_3278
	s_mov_b32 s24, 1
	s_branch .LBB0_3271

.LBB0_3330:
	s_or_b64 exec, exec, s[10:11]
	v_cvt_f32_u32_e32 v5, v3
	s_waitcnt vmcnt(0)
	v_readfirstlane_b32 s8, v4
	buffer_inv sc1
	s_add_u32 s6, s6, 0x2400
	s_addc_u32 s7, s7, 0
	v_add_u32_e32 v6, s8, v2
	v_add_u32_e32 v4, 1, v6
	v_mul_u32_u24_e32 v3, 38, v3
	v_mov_b32_e32 v2, 37
	v_cmp_ne_u32_e32 vcc, v4, v3
	s_and_saveexec_b64 s[8:9], vcc
	s_xor_b64 s[8:9], exec, s[8:9]
	s_cbranch_execz .LBB0_3344
	s_waitcnt lgkmcnt(0)
	v_mov_b32_e32 v1, 0
	global_load_dword v3, v1, s[6:7] sc1
	s_waitcnt vmcnt(0)
	v_cmp_eq_u32_e32 vcc, v3, v2
	s_and_saveexec_b64 s[10:11], vcc
	s_cbranch_execz .LBB0_3343
	s_mov_b32 s22, 1
	s_mov_b64 s[12:13], 0
	s_branch .LBB0_3334

.LBB0_3347:
	s_or_b64 exec, exec, s[10:11]
	v_cvt_f32_u32_e32 v4, v1
	s_waitcnt vmcnt(0)
	v_readfirstlane_b32 s10, v3
	s_add_u32 s8, s94, 0x7500
	s_addc_u32 s9, s95, 0
	s_mov_b64 s[12:13], -1
	v_add_u32_e32 v2, s10, v2
	v_add_u32_e32 v2, 1, v2
	v_mul_u32_u24_e32 v1, 38, v1
	v_mov_b32_e32 v4, 37
	v_cmp_ne_u32_e32 vcc, v2, v1
	v_mov_b64_e32 v[2:3], s[8:9]
	s_and_saveexec_b64 s[10:11], vcc
	s_cbranch_execz .LBB0_3359
	v_mov_b32_e32 v1, 0
	global_load_dword v2, v1, s[100:101] sc1
	s_mov_b64 s[14:15], 0
	s_waitcnt vmcnt(0)
	v_cmp_lt_u32_e32 vcc, v2, v18
	s_and_saveexec_b64 s[12:13], vcc
	s_cbranch_execz .LBB0_3358
	s_mov_b32 s24, 1
	s_branch .LBB0_3351

.LBB0_3424:
	s_or_b64 exec, exec, s[10:11]
	v_cvt_f32_u32_e32 v5, v3
	s_waitcnt vmcnt(0)
	v_readfirstlane_b32 s3, v4
	buffer_inv sc1
	s_add_u32 s6, s6, 0x2400
	s_addc_u32 s7, s7, 0
	v_add_u32_e32 v6, s3, v2
	v_add_u32_e32 v4, 1, v6
	v_mul_u32_u24_e32 v3, 39, v3
	v_mov_b32_e32 v2, 38
	v_cmp_ne_u32_e32 vcc, v4, v3
	s_and_saveexec_b64 s[8:9], vcc
	s_xor_b64 s[8:9], exec, s[8:9]
	s_cbranch_execz .LBB0_3438
	s_waitcnt lgkmcnt(0)
	v_mov_b32_e32 v1, 0
	global_load_dword v3, v1, s[6:7] sc1
	s_waitcnt vmcnt(0)
	v_cmp_eq_u32_e32 vcc, v3, v2
	s_and_saveexec_b64 s[10:11], vcc
	s_cbranch_execz .LBB0_3437
	s_mov_b32 s3, 1
	s_mov_b64 s[12:13], 0
	s_branch .LBB0_3428

.LBB0_3441:
	s_or_b64 exec, exec, s[10:11]
	v_cvt_f32_u32_e32 v4, v1
	s_waitcnt vmcnt(0)
	v_readfirstlane_b32 s3, v3
	s_add_u32 s8, s94, 0x7500
	s_addc_u32 s9, s95, 0
	s_mov_b64 s[12:13], -1
	v_add_u32_e32 v2, s3, v2
	v_add_u32_e32 v2, 1, v2
	v_mul_u32_u24_e32 v1, 39, v1
	v_mov_b32_e32 v4, 38
	v_cmp_ne_u32_e32 vcc, v2, v1
	v_mov_b64_e32 v[2:3], s[8:9]
	s_and_saveexec_b64 s[10:11], vcc
	s_cbranch_execz .LBB0_3453
	v_mov_b32_e32 v1, 0
	global_load_dword v2, v1, s[100:101] sc1
	s_mov_b64 s[14:15], 0
	s_waitcnt vmcnt(0)
	v_cmp_lt_u32_e32 vcc, v2, v18
	s_and_saveexec_b64 s[12:13], vcc
	s_cbranch_execz .LBB0_3452
	s_mov_b32 s3, 1
	s_branch .LBB0_3445

.LBB0_3522:
	s_or_b64 exec, exec, s[8:9]
	v_cvt_f32_u32_e32 v5, v3
	s_waitcnt vmcnt(0)
	v_readfirstlane_b32 s6, v4
	buffer_inv sc1
	s_add_u32 s4, s4, 0x2400
	s_addc_u32 s5, s5, 0
	v_add_u32_e32 v6, s6, v2
	v_add_u32_e32 v4, 1, v6
	v_mul_u32_u24_e32 v3, 40, v3
	v_mov_b32_e32 v2, 39
	v_cmp_ne_u32_e32 vcc, v4, v3
	s_and_saveexec_b64 s[6:7], vcc
	s_xor_b64 s[6:7], exec, s[6:7]
	s_cbranch_execz .LBB0_3536
	s_waitcnt lgkmcnt(0)
	v_mov_b32_e32 v1, 0
	global_load_dword v3, v1, s[4:5] sc1
	s_waitcnt vmcnt(0)
	v_cmp_eq_u32_e32 vcc, v3, v2
	s_and_saveexec_b64 s[8:9], vcc
	s_cbranch_execz .LBB0_3535
	s_mov_b32 s20, 1
	s_mov_b64 s[10:11], 0
	s_branch .LBB0_3526

.LBB0_3539:
	s_or_b64 exec, exec, s[8:9]
	v_cvt_f32_u32_e32 v4, v1
	s_waitcnt vmcnt(0)
	v_readfirstlane_b32 s8, v3
	s_add_u32 s6, s94, 0x7500
	s_addc_u32 s7, s95, 0
	s_mov_b64 s[10:11], -1
	v_add_u32_e32 v2, s8, v2
	v_add_u32_e32 v2, 1, v2
	v_mul_u32_u24_e32 v1, 40, v1
	v_mov_b32_e32 v4, 39
	v_cmp_ne_u32_e32 vcc, v2, v1
	v_mov_b64_e32 v[2:3], s[6:7]
	s_and_saveexec_b64 s[8:9], vcc
	s_cbranch_execz .LBB0_3551
	v_mov_b32_e32 v1, 0
	global_load_dword v2, v1, s[100:101] sc1
	s_mov_b64 s[12:13], 0
	s_waitcnt vmcnt(0)
	v_cmp_lt_u32_e32 vcc, v2, v18
	s_and_saveexec_b64 s[10:11], vcc
	s_cbranch_execz .LBB0_3550
	s_mov_b32 s22, 1
	s_branch .LBB0_3543

.LBB0_3592:
	s_or_b64 exec, exec, s[8:9]
	v_cvt_f32_u32_e32 v4, v2
	s_waitcnt vmcnt(0)
	v_readfirstlane_b32 s6, v3
	buffer_inv sc1
	s_add_u32 s4, s4, 0x2400
	s_addc_u32 s5, s5, 0
	v_add_u32_e32 v5, s6, v1
	v_add_u32_e32 v3, 1, v5
	v_mul_u32_u24_e32 v2, 41, v2
	v_mov_b32_e32 v1, 40
	v_cmp_ne_u32_e32 vcc, v3, v2
	s_and_saveexec_b64 s[6:7], vcc
	s_xor_b64 s[6:7], exec, s[6:7]
	s_cbranch_execz .LBB0_3606
	s_waitcnt lgkmcnt(0)
	v_mov_b32_e32 v0, 0
	global_load_dword v2, v0, s[4:5] sc1
	s_waitcnt vmcnt(0)
	v_cmp_eq_u32_e32 vcc, v2, v1
	s_and_saveexec_b64 s[8:9], vcc
	s_cbranch_execz .LBB0_3605
	s_mov_b32 s20, 1
	s_mov_b64 s[10:11], 0
	s_branch .LBB0_3596

.LBB0_3609:
	s_or_b64 exec, exec, s[8:9]
	v_cvt_f32_u32_e32 v3, v0
	s_waitcnt vmcnt(0)
	v_readfirstlane_b32 s8, v2
	s_add_u32 s6, s94, 0x7500
	s_addc_u32 s7, s95, 0
	s_mov_b64 s[10:11], -1
	v_add_u32_e32 v1, s8, v1
	v_add_u32_e32 v1, 1, v1
	v_mul_u32_u24_e32 v0, 41, v0
	v_mov_b32_e32 v2, 40
	v_cmp_ne_u32_e32 vcc, v1, v0
	v_mov_b64_e32 v[0:1], s[6:7]
	s_and_saveexec_b64 s[8:9], vcc
	s_cbranch_execz .LBB0_3621
	v_mov_b32_e32 v0, 0
	global_load_dword v1, v0, s[100:101] sc1
	s_mov_b64 s[12:13], 0
	s_waitcnt vmcnt(0)
	v_cmp_lt_u32_e32 vcc, v1, v18
	s_and_saveexec_b64 s[10:11], vcc
	s_cbranch_execz .LBB0_3620
	s_mov_b32 s22, 1
	s_branch .LBB0_3613
